# speedup vs baseline: 1.0038x; 1.0009x over previous
; __device__ __forceinline__ void mixerA_tile(const Params& p, int tile, char* smem) {
;     ...
;   for (int r = 0; r < 16; ++r) {
;     int t = wid * 16 + r;
;     const u16* vp = Z + (tok0 + t) * LDZ0 + 1024 + lane * 16;
;     float f[16];
;     unpack8(*(const uint4*)vp, f);
;     unpack8(*(const uint4*)(vp + 8), f + 8);
.LBB0_185:
	s_and_b64 vcc, exec, s[0:1]
	s_cbranch_vccz .LBB0_211
	s_waitcnt vmcnt(11)
	v_xor_b32_e32 v4, 32, v148
	v_cmp_lt_i32_e32 vcc, v4, v150
	v_mov_b32_e32 v1, v194
	s_waitcnt vmcnt(9)
	v_mov_b32_e32 v15, v0
	v_cndmask_b32_e32 v4, v148, v4, vcc
	v_lshlrev_b32_e32 v6, 2, v4
	v_xor_b32_e32 v4, 16, v148
	v_cmp_lt_i32_e32 vcc, v4, v150
	v_ashrrev_i32_e32 v3, 6, v1
	v_lshlrev_b32_e32 v20, 4, v3
	v_cndmask_b32_e32 v4, v148, v4, vcc
	v_cmp_lt_i32_e32 vcc, v153, v150
	v_lshlrev_b32_e32 v7, 2, v4
	v_and_b32_e32 v2, 63, v1
	v_cndmask_b32_e32 v4, v148, v153, vcc
	v_cmp_lt_i32_e32 vcc, v152, v150
	v_lshlrev_b32_e32 v8, 2, v4
	v_ashrrev_i32_e32 v21, 31, v20
	v_cndmask_b32_e32 v4, v148, v152, vcc
	v_cmp_lt_i32_e32 vcc, v151, v150
	v_lshlrev_b32_e32 v9, 2, v4
	v_lshlrev_b32_e32 v14, 5, v2
	v_cndmask_b32_e32 v4, v148, v151, vcc
	v_cmp_lt_i32_e32 vcc, v149, v150
	v_lshlrev_b32_e32 v10, 2, v4
	v_readlane_b32 s16, v248, 45
	v_cndmask_b32_e32 v4, v148, v149, vcc
	v_lshlrev_b32_e32 v11, 2, v4
	v_and_b32_e32 v4, 0xffffffc0, v1
	v_add_u32_e32 v12, 0, v4
	v_lshl_add_u64 v[4:5], v[20:21], 0, s[34:35]
	v_mad_u64_u32 v[14:15], s[0:1], v4, s77, v[14:15]
	v_mad_i32_i24 v15, v5, s77, v15
	v_readlane_b32 s24, v248, 53
	v_readlane_b32 s25, v248, 54
	v_cmp_eq_u32_e32 vcc, 0, v2
	s_mov_b64 s[4:5], 0
	v_lshl_add_u64 v[4:5], s[24:25], 0, v[14:15]
	v_readlane_b32 s17, v248, 46
	v_readlane_b32 s18, v248, 47
	v_readlane_b32 s19, v248, 48
	v_readlane_b32 s20, v248, 49
	v_readlane_b32 s21, v248, 50
	v_readlane_b32 s22, v248, 51
	v_readlane_b32 s23, v248, 52
	v_readlane_b32 s26, v248, 55
	v_readlane_b32 s27, v248, 56
	v_readlane_b32 s28, v248, 57
	v_readlane_b32 s29, v248, 58
	v_readlane_b32 s30, v248, 59
	v_readlane_b32 s31, v248, 60
	v_lshl_add_u64 v[242:243], v[4:5], 0, s[4:5]
	v_mov_b32_e32 v244, 0x3600
	v_mov_b32_e32 v245, 0
	global_load_dwordx4 v[234:237], v[242:243], off offset:2048
	global_load_dwordx4 v[238:241], v[242:243], off offset:2064
	s_branch .LBB0_188

; __device__ __forceinline__ void mixerA_tile(const Params& p, int tile, char* smem) {
;     ...
;   for (int r = 0; r < 16; ++r) {
;     int t = wid * 16 + r;
;     const u16* vp = Z + (tok0 + t) * LDZ0 + 1024 + lane * 16;
;     float f[16];
;     unpack8(*(const uint4*)vp, f);
;     unpack8(*(const uint4*)(vp + 8), f + 8);
;     float s = 0.f;
; #pragma unroll
;     for (int i = 0; i < 16; ++i) { f[i] = geluf_(f[i]); s += f[i]; }
;     s = wave_sum(s);
;     float mean = s * (1.f / 1024.f);
;     float d2 = 0.f;
; #pragma unroll
;     for (int i = 0; i < 16; ++i) { float d = f[i] - mean; d2 += d * d; }
;     d2 = wave_sum(d2);
;     if (lane == 0) { mu[t] = mean; rs[t] = rsqrtf(d2 * (1.f / 1024.f) + EPS); }
;   }
.LBB0_188:
	s_waitcnt vmcnt(0)
	v_mov_b64_e32 v[14:15], v[234:235]
	v_mov_b64_e32 v[16:17], v[236:237]
	v_mov_b64_e32 v[22:23], v[238:239]
	v_mov_b64_e32 v[24:25], v[240:241]
	v_lshl_add_u64 v[242:243], v[242:243], 0, v[244:245]
	s_waitcnt lgkmcnt(0)
	global_load_dwordx4 v[234:237], v[242:243], off offset:2048
	global_load_dwordx4 v[238:241], v[242:243], off offset:2064
	v_lshlrev_b32_e32 v18, 16, v14
	v_and_b32_e32 v14, 0xffff0000, v14
	v_mul_f32_e32 v13, 0x3dd2d3e7, v18
	v_lshlrev_b32_e32 v19, 16, v15
	v_mul_f32_e32 v31, 0x3dd2d3e7, v14
	v_fma_f32 v13, -v13, v18, s10
	v_and_b32_e32 v15, 0xffff0000, v15
	v_mul_f32_e32 v32, 0x3dd2d3e7, v19
	v_fma_f32 v31, -v31, v14, s10
	v_mul_f32_e32 v13, v13, v18
	v_lshlrev_b32_e32 v21, 16, v16
	v_mul_f32_e32 v33, 0x3dd2d3e7, v15
	v_fma_f32 v32, -v32, v19, s10
	v_mul_f32_e32 v31, v31, v14
	v_exp_f32_e32 v13, v13
	v_and_b32_e32 v16, 0xffff0000, v16
	v_mul_f32_e32 v34, 0x3dd2d3e7, v21
	v_fma_f32 v33, -v33, v15, s10
	v_mul_f32_e32 v32, v32, v19
	v_exp_f32_e32 v31, v31
	v_lshlrev_b32_e32 v26, 16, v17
	v_mul_f32_e32 v35, 0x3dd2d3e7, v16
	v_fma_f32 v34, -v34, v21, s10
	v_mul_f32_e32 v33, v33, v15
	v_exp_f32_e32 v32, v32
	v_and_b32_e32 v17, 0xffff0000, v17
	v_mul_f32_e32 v36, 0x3dd2d3e7, v26
	v_fma_f32 v35, -v35, v16, s10
	v_mul_f32_e32 v34, v34, v21
	v_exp_f32_e32 v33, v33
	s_nop 0
	v_lshlrev_b32_e32 v27, 16, v22
	v_mul_f32_e32 v37, 0x3dd2d3e7, v17
	v_fma_f32 v36, -v36, v26, s10
	v_mul_f32_e32 v35, v35, v16
	v_exp_f32_e32 v34, v34
	v_add_f32_e32 v13, 1.0, v13
	v_and_b32_e32 v22, 0xffff0000, v22
	v_mul_f32_e32 v38, 0x3dd2d3e7, v27
	v_fma_f32 v37, -v37, v17, s10
	v_mul_f32_e32 v36, v36, v26
	v_exp_f32_e32 v35, v35
	v_add_f32_e32 v31, 1.0, v31
	v_rcp_f32_e32 v43, v13
	v_lshlrev_b32_e32 v28, 16, v23
	v_mul_f32_e32 v39, 0x3dd2d3e7, v22
	v_fma_f32 v38, -v38, v27, s10
	v_mul_f32_e32 v37, v37, v17
	v_exp_f32_e32 v36, v36
	v_add_f32_e32 v32, 1.0, v32
	v_rcp_f32_e32 v31, v31
	v_and_b32_e32 v23, 0xffff0000, v23
	v_mul_f32_e32 v40, 0x3dd2d3e7, v28
	v_fma_f32 v39, -v39, v22, s10
	v_mul_f32_e32 v38, v38, v27
	v_exp_f32_e32 v37, v37
	v_add_f32_e32 v33, 1.0, v33
	v_rcp_f32_e32 v32, v32
	v_lshlrev_b32_e32 v29, 16, v24
	v_mul_f32_e32 v41, 0x3dd2d3e7, v23
	v_fma_f32 v40, -v40, v28, s10
	v_mul_f32_e32 v39, v39, v22
	v_exp_f32_e32 v38, v38
	v_add_f32_e32 v34, 1.0, v34
	v_rcp_f32_e32 v33, v33
	v_and_b32_e32 v24, 0xffff0000, v24
	v_mul_f32_e32 v42, 0x3dd2d3e7, v29
	v_fma_f32 v41, -v41, v23, s10
	v_mul_f32_e32 v40, v40, v28
	v_exp_f32_e32 v39, v39
	v_add_f32_e32 v35, 1.0, v35
	v_rcp_f32_e32 v34, v34
	v_fma_f32 v13, v43, v18, 0
	v_lshlrev_b32_e32 v30, 16, v25
	v_fma_f32 v42, -v42, v29, s10
	v_mul_f32_e32 v41, v41, v23
	v_exp_f32_e32 v40, v40
	v_add_f32_e32 v36, 1.0, v36
	v_rcp_f32_e32 v35, v35
	v_fmac_f32_e32 v13, v31, v14
	v_mul_f32_e32 v44, 0x3dd2d3e7, v24
	v_and_b32_e32 v25, 0xffff0000, v25
	v_mul_f32_e32 v42, v42, v29
	v_exp_f32_e32 v41, v41
	v_add_f32_e32 v37, 1.0, v37
	v_rcp_f32_e32 v36, v36
	v_fmac_f32_e32 v13, v32, v19
	v_fma_f32 v44, -v44, v24, s10
	v_mul_f32_e32 v45, 0x3dd2d3e7, v30
	v_add_f32_e32 v38, 1.0, v38
	v_rcp_f32_e32 v37, v37
	v_fmac_f32_e32 v13, v33, v15
	v_exp_f32_e32 v42, v42
	v_mul_f32_e32 v44, v44, v24
	v_fma_f32 v45, -v45, v30, s10
	v_mul_f32_e32 v46, 0x3dd2d3e7, v25
	v_add_f32_e32 v39, 1.0, v39
	v_rcp_f32_e32 v38, v38
	v_fmac_f32_e32 v13, v34, v21
	v_exp_f32_e32 v44, v44
	v_mul_f32_e32 v45, v45, v30
	v_fma_f32 v46, -v46, v25, s10
	v_add_f32_e32 v40, 1.0, v40
	v_rcp_f32_e32 v39, v39
	v_fmac_f32_e32 v13, v35, v16
	v_exp_f32_e32 v45, v45
	v_mul_f32_e32 v46, v46, v25
	v_add_f32_e32 v41, 1.0, v41
	v_rcp_f32_e32 v40, v40
	v_fmac_f32_e32 v13, v36, v26
	v_exp_f32_e32 v46, v46
	v_rcp_f32_e32 v41, v41
	v_fmac_f32_e32 v13, v37, v17
	v_add_f32_e32 v42, 1.0, v42
	v_fmac_f32_e32 v13, v38, v27
	v_rcp_f32_e32 v42, v42
	v_add_f32_e32 v44, 1.0, v44
	v_fmac_f32_e32 v13, v39, v22
	v_rcp_f32_e32 v44, v44
	v_add_f32_e32 v45, 1.0, v45
	v_fmac_f32_e32 v13, v40, v28
	v_rcp_f32_e32 v45, v45
	v_add_f32_e32 v46, 1.0, v46
	v_fmac_f32_e32 v13, v41, v23
	v_rcp_f32_e32 v46, v46
	v_fmac_f32_e32 v13, v42, v29
	v_fmac_f32_e32 v13, v44, v24
	v_fmac_f32_e32 v13, v45, v30
	v_fmac_f32_e32 v13, v46, v25
	ds_bpermute_b32 v47, v6, v13
	s_waitcnt lgkmcnt(0)
	v_add_f32_e32 v13, v13, v47
	ds_bpermute_b32 v47, v7, v13
	s_waitcnt lgkmcnt(0)
	v_add_f32_e32 v13, v13, v47
	ds_bpermute_b32 v47, v8, v13
	s_waitcnt lgkmcnt(0)
	v_add_f32_e32 v13, v13, v47
	ds_bpermute_b32 v47, v9, v13
	s_waitcnt lgkmcnt(0)
	v_add_f32_e32 v13, v13, v47
	ds_bpermute_b32 v47, v10, v13
	s_waitcnt lgkmcnt(0)
	v_add_f32_e32 v13, v13, v47
	ds_bpermute_b32 v47, v11, v13
	s_waitcnt lgkmcnt(0)
	v_add_f32_e32 v13, v13, v47
	v_mul_f32_e32 v13, 0x3a800000, v13
	v_fma_f32 v14, v31, v14, -v13
	v_fma_f32 v18, v43, v18, -v13
	v_mul_f32_e32 v14, v14, v14
	v_fma_f32 v19, v32, v19, -v13
	v_fmac_f32_e32 v14, v18, v18
	v_fma_f32 v15, v33, v15, -v13
	v_fmac_f32_e32 v14, v19, v19
	v_fmac_f32_e32 v14, v15, v15
	v_fma_f32 v15, v34, v21, -v13
	v_fmac_f32_e32 v14, v15, v15
	v_fma_f32 v15, v35, v16, -v13
	v_fmac_f32_e32 v14, v15, v15
	v_fma_f32 v15, v36, v26, -v13
	v_fmac_f32_e32 v14, v15, v15
	v_fma_f32 v15, v37, v17, -v13
	v_fmac_f32_e32 v14, v15, v15
	v_fma_f32 v15, v38, v27, -v13
	v_fmac_f32_e32 v14, v15, v15
	v_fma_f32 v15, v39, v22, -v13
	v_fmac_f32_e32 v14, v15, v15
	v_fma_f32 v15, v40, v28, -v13
	v_fmac_f32_e32 v14, v15, v15
	v_fma_f32 v15, v41, v23, -v13
	v_fmac_f32_e32 v14, v15, v15
	v_fma_f32 v15, v42, v29, -v13
	v_fmac_f32_e32 v14, v15, v15
	v_fma_f32 v15, v44, v24, -v13
	v_fmac_f32_e32 v14, v15, v15
	v_fma_f32 v15, v45, v30, -v13
	v_fmac_f32_e32 v14, v15, v15
	v_fma_f32 v15, v46, v25, -v13
	v_fmac_f32_e32 v14, v15, v15
	ds_bpermute_b32 v15, v6, v14
	s_waitcnt lgkmcnt(0)
	v_add_f32_e32 v14, v14, v15
	ds_bpermute_b32 v15, v7, v14
	s_waitcnt lgkmcnt(0)
	v_add_f32_e32 v14, v14, v15
	ds_bpermute_b32 v15, v8, v14
	s_waitcnt lgkmcnt(0)
	v_add_f32_e32 v14, v14, v15
	ds_bpermute_b32 v15, v9, v14
	s_waitcnt lgkmcnt(0)
	v_add_f32_e32 v14, v14, v15
	ds_bpermute_b32 v15, v10, v14
	s_waitcnt lgkmcnt(0)
	v_add_f32_e32 v14, v14, v15
	ds_bpermute_b32 v15, v11, v14
	s_and_saveexec_b64 s[6:7], vcc
	s_cbranch_execz .LBB0_187
	s_waitcnt lgkmcnt(0)
	v_add_f32_e32 v14, v14, v15
	v_fmamk_f32 v14, v14, 0x3a800000, v107
	v_mul_f32_e32 v15, 0x4b800000, v14
	v_cmp_gt_f32_e64 s[0:1], s76, v14
	s_nop 1
	v_cndmask_b32_e64 v14, v14, v15, s[0:1]
	v_rsq_f32_e32 v14, v14
	s_nop 0
	v_mul_f32_e32 v15, 0x45800000, v14
	v_cndmask_b32_e64 v14, v14, v15, s[0:1]
	ds_write2st64_b32 v12, v13, v14 offset1:2
	s_branch .LBB0_187
